# NA tile loop: rel-pos-bias lookups use one base register + DS immediate offsets (4 instrs per element instead of 8)
# speedup vs baseline: 1.0139x; 1.0014x over previous
.LBB0_283:
	s_andn2_b64 vcc, exec, s[10:11]
	s_cbranch_vccnz .LBB0_280
	s_add_i32 s10, s24, 0xffffc000
	s_and_b32 s10, s10, 0x4000
	v_add3_u32 v94, s10, v109, v108
	v_add3_u32 v95, s10, v110, v108
	v_add3_u32 v130, s10, v111, v108
	v_add3_u32 v131, s10, v112, v108
	ds_read_b128 v[148:151], v94
	ds_read_b128 v[152:155], v95
	ds_read_b128 v[156:159], v130
	ds_read_b128 v[160:163], v131
	ds_read_b128 v[164:167], v94 offset:4096
	ds_read_b128 v[168:171], v95 offset:4096
	ds_read_b128 v[172:175], v130 offset:4096
	ds_read_b128 v[176:179], v131 offset:4096
	s_andn2_b64 vcc, exec, s[72:73]
	s_waitcnt lgkmcnt(7)
	v_mfma_f32_32x32x16_bf16 v[34:49], v[148:151], v[78:81], 0
	s_waitcnt lgkmcnt(6)
	v_mfma_f32_32x32x16_bf16 v[34:49], v[152:155], v[74:77], v[34:49]
	s_waitcnt lgkmcnt(5)
	v_mfma_f32_32x32x16_bf16 v[34:49], v[156:159], v[70:73], v[34:49]
	s_waitcnt lgkmcnt(4)
	v_mfma_f32_32x32x16_bf16 v[34:49], v[160:163], v[66:69], v[34:49]
	s_waitcnt lgkmcnt(3)
	v_mfma_f32_32x32x16_bf16 v[50:65], v[164:167], v[78:81], 0
	s_waitcnt lgkmcnt(2)
	v_mfma_f32_32x32x16_bf16 v[50:65], v[168:171], v[74:77], v[50:65]
	s_waitcnt lgkmcnt(1)
	v_mfma_f32_32x32x16_bf16 v[50:65], v[172:175], v[70:73], v[50:65]
	s_waitcnt lgkmcnt(0)
	v_mfma_f32_32x32x16_bf16 v[50:65], v[176:179], v[66:69], v[50:65]
	s_cbranch_vccnz .LBB0_286
	v_cmp_ge_i32_e32 vcc, s3, v98
	v_cmp_lt_i32_e64 s[72:73], s3, v106
	s_and_b64 s[26:27], vcc, s[72:73]
	s_add_i32 s11, s3, 1
	v_cmp_ge_i32_e32 vcc, s11, v98
	v_cmp_lt_i32_e64 s[72:73], s11, v106
	s_and_b64 s[72:73], vcc, s[72:73]
	v_add_u32_e32 v94, s29, v125
	v_lshlrev_b32_e32 v95, 2, v94
	v_add_u32_e32 v95, 0x7cbc, v95
	ds_read_b32 v148, v95
	ds_read_b32 v149, v95 offset:4
	ds_read_b32 v150, v95 offset:8
	ds_read_b32 v151, v95 offset:12
	ds_read_b32 v152, v95 offset:32
	ds_read_b32 v153, v95 offset:36
	ds_read_b32 v154, v95 offset:40
	ds_read_b32 v155, v95 offset:44
	ds_read_b32 v156, v95 offset:64
	ds_read_b32 v157, v95 offset:68
	ds_read_b32 v158, v95 offset:72
	ds_read_b32 v159, v95 offset:76
	s_waitcnt lgkmcnt(11)
	s_and_b64 vcc, s[26:27], s[68:69]
	v_add_f32_e32 v34, v34, v148
	v_cndmask_b32_e32 v34, v213, v34, vcc
	ds_read_b32 v148, v95 offset:96
	s_waitcnt lgkmcnt(11)
	s_and_b64 vcc, s[26:27], s[66:67]
	v_add_f32_e32 v35, v35, v149
	v_cndmask_b32_e32 v35, v213, v35, vcc
	ds_read_b32 v149, v95 offset:100
	s_waitcnt lgkmcnt(11)
	s_and_b64 vcc, s[26:27], s[64:65]
	v_add_f32_e32 v36, v36, v150
	v_cndmask_b32_e32 v36, v213, v36, vcc
	ds_read_b32 v150, v95 offset:104
	s_waitcnt lgkmcnt(11)
	s_and_b64 vcc, s[26:27], s[62:63]
	v_add_f32_e32 v37, v37, v151
	v_cndmask_b32_e32 v37, v213, v37, vcc
	ds_read_b32 v151, v95 offset:108
	s_waitcnt lgkmcnt(11)
	s_and_b64 vcc, s[26:27], s[60:61]
	v_add_f32_e32 v38, v38, v152
	v_cndmask_b32_e32 v38, v213, v38, vcc
	ds_read_b32 v152, v95 offset:128
	s_waitcnt lgkmcnt(11)
	s_and_b64 vcc, s[26:27], s[58:59]
	v_add_f32_e32 v39, v39, v153
	v_cndmask_b32_e32 v39, v213, v39, vcc
	ds_read_b32 v153, v95 offset:132
	s_waitcnt lgkmcnt(11)
	s_and_b64 vcc, s[26:27], s[56:57]
	v_add_f32_e32 v40, v40, v154
	v_cndmask_b32_e32 v40, v213, v40, vcc
	ds_read_b32 v154, v95 offset:136
	s_waitcnt lgkmcnt(11)
	s_and_b64 vcc, s[26:27], s[54:55]
	v_add_f32_e32 v41, v41, v155
	v_cndmask_b32_e32 v41, v213, v41, vcc
	ds_read_b32 v155, v95 offset:140
	s_waitcnt lgkmcnt(11)
	s_and_b64 vcc, s[26:27], s[52:53]
	v_add_f32_e32 v42, v42, v156
	v_cndmask_b32_e32 v42, v213, v42, vcc
	ds_read_b32 v156, v95 offset:160
	s_waitcnt lgkmcnt(11)
	s_and_b64 vcc, s[26:27], s[50:51]
	v_add_f32_e32 v43, v43, v157
	v_cndmask_b32_e32 v43, v213, v43, vcc
	ds_read_b32 v157, v95 offset:164
	s_waitcnt lgkmcnt(11)
	s_and_b64 vcc, s[26:27], s[48:49]
	v_add_f32_e32 v44, v44, v158
	v_cndmask_b32_e32 v44, v213, v44, vcc
	ds_read_b32 v158, v95 offset:168
	s_waitcnt lgkmcnt(11)
	s_and_b64 vcc, s[26:27], s[46:47]
	v_add_f32_e32 v45, v45, v159
	v_cndmask_b32_e32 v45, v213, v45, vcc
	ds_read_b32 v159, v95 offset:172
	s_waitcnt lgkmcnt(11)
	s_and_b64 vcc, s[26:27], s[44:45]
	v_add_f32_e32 v46, v46, v148
	v_cndmask_b32_e32 v46, v213, v46, vcc
	ds_read_b32 v148, v95 offset:192
	s_waitcnt lgkmcnt(11)
	s_and_b64 vcc, s[26:27], s[42:43]
	v_add_f32_e32 v47, v47, v149
	v_cndmask_b32_e32 v47, v213, v47, vcc
	ds_read_b32 v149, v95 offset:196
	s_waitcnt lgkmcnt(11)
	s_and_b64 vcc, s[26:27], s[40:41]
	v_add_f32_e32 v48, v48, v150
	v_cndmask_b32_e32 v48, v213, v48, vcc
	ds_read_b32 v150, v95 offset:200
	s_waitcnt lgkmcnt(11)
	s_and_b64 vcc, s[26:27], s[38:39]
	v_add_f32_e32 v49, v49, v151
	v_cndmask_b32_e32 v49, v213, v49, vcc
	ds_read_b32 v151, v95 offset:204
	s_waitcnt lgkmcnt(11)
	s_and_b64 vcc, s[72:73], s[68:69]
	v_add_f32_e32 v50, v50, v152
	v_cndmask_b32_e32 v50, v213, v50, vcc
	ds_read_b32 v152, v95 offset:224
	s_waitcnt lgkmcnt(11)
	s_and_b64 vcc, s[72:73], s[66:67]
	v_add_f32_e32 v51, v51, v153
	v_cndmask_b32_e32 v51, v213, v51, vcc
	ds_read_b32 v153, v95 offset:228
	s_waitcnt lgkmcnt(11)
	s_and_b64 vcc, s[72:73], s[64:65]
	v_add_f32_e32 v52, v52, v154
	v_cndmask_b32_e32 v52, v213, v52, vcc
	ds_read_b32 v154, v95 offset:232
	s_waitcnt lgkmcnt(11)
	s_and_b64 vcc, s[72:73], s[62:63]
	v_add_f32_e32 v53, v53, v155
	v_cndmask_b32_e32 v53, v213, v53, vcc
	ds_read_b32 v155, v95 offset:236
	s_waitcnt lgkmcnt(11)
	s_and_b64 vcc, s[72:73], s[60:61]
	v_add_f32_e32 v54, v54, v156
	v_cndmask_b32_e32 v54, v213, v54, vcc
	s_waitcnt lgkmcnt(10)
	s_and_b64 vcc, s[72:73], s[58:59]
	v_add_f32_e32 v55, v55, v157
	v_cndmask_b32_e32 v55, v213, v55, vcc
	s_waitcnt lgkmcnt(9)
	s_and_b64 vcc, s[72:73], s[56:57]
	v_add_f32_e32 v56, v56, v158
	v_cndmask_b32_e32 v56, v213, v56, vcc
	s_waitcnt lgkmcnt(8)
	s_and_b64 vcc, s[72:73], s[54:55]
	v_add_f32_e32 v57, v57, v159
	v_cndmask_b32_e32 v57, v213, v57, vcc
	s_waitcnt lgkmcnt(7)
	s_and_b64 vcc, s[72:73], s[52:53]
	v_add_f32_e32 v58, v58, v148
	v_cndmask_b32_e32 v58, v213, v58, vcc
	s_waitcnt lgkmcnt(6)
	s_and_b64 vcc, s[72:73], s[50:51]
	v_add_f32_e32 v59, v59, v149
	v_cndmask_b32_e32 v59, v213, v59, vcc
	s_waitcnt lgkmcnt(5)
	s_and_b64 vcc, s[72:73], s[48:49]
	v_add_f32_e32 v60, v60, v150
	v_cndmask_b32_e32 v60, v213, v60, vcc
	s_waitcnt lgkmcnt(4)
	s_and_b64 vcc, s[72:73], s[46:47]
	v_add_f32_e32 v61, v61, v151
	v_cndmask_b32_e32 v61, v213, v61, vcc
	s_waitcnt lgkmcnt(3)
	s_and_b64 vcc, s[72:73], s[44:45]
	v_add_f32_e32 v62, v62, v152
	v_cndmask_b32_e32 v62, v213, v62, vcc
	s_waitcnt lgkmcnt(2)
	s_and_b64 vcc, s[72:73], s[42:43]
	v_add_f32_e32 v63, v63, v153
	v_cndmask_b32_e32 v63, v213, v63, vcc
	s_waitcnt lgkmcnt(1)
	s_and_b64 vcc, s[72:73], s[40:41]
	v_add_f32_e32 v64, v64, v154
	v_cndmask_b32_e32 v64, v213, v64, vcc
	s_waitcnt lgkmcnt(0)
	s_and_b64 vcc, s[72:73], s[38:39]
	v_add_f32_e32 v65, v65, v155
	v_cndmask_b32_e32 v65, v213, v65, vcc
